# leading wave half (wr==0) raised from its epilogue until its next MMA segment in proj/gates/ffn-up GEMMs; P3/rmsnorm raise code resets to 0 first
# speedup vs baseline: 1.0025x; 1.0025x over previous
; __global__ void __launch_bounds__(512, 2) fwd_megakernel(Params P) {
;     ...
;         rmsnorm_rows<true>(xin, P.in[I_N1G] + l * DM, hbuf, P, l, lds, gw, NGW, lane);
.LBB0_76:
	v_readlane_b32 s4, v254, 9
	v_mov_b32_e32 v18, v180
	s_mov_b32 s12, s4
	s_waitcnt lgkmcnt(0)
	s_barrier
	s_setprio 0
	v_readfirstlane_b32 s3, v180
	s_nop 3
	s_cmp_ge_u32 s3, 0x100
	s_cbranch_scc0 .Lprio_p1
	s_setprio 1

; #define PG8_BAR __builtin_amdgcn_s_barrier()
; #define PG8_BAR __builtin_amdgcn_s_barrier()
; template <class Epi, class Sched>
; __device__ __forceinline__ void gemm_phase(LAS unsigned char* lds, const Gemm g, const Sched& S, const Epi& E) {
;     ...
;         if (wr == 0) PG8_BAR;
;         E(acc, cur, wr, wc, fr, fq);
.LBB0_185:
	s_and_b64 vcc, exec, s[8:9]
	s_cbranch_vccz .Leprio_proj
	s_setprio 1

.LBB0_340:
	s_or_b64 exec, exec, s[2:3]
	v_readlane_b32 s2, v254, 9
	v_mov_b32_e32 v1, v180
	s_mov_b32 s5, s2
	s_waitcnt lgkmcnt(0)
	s_barrier
	s_setprio 0
	v_readfirstlane_b32 s2, v180
	s_nop 3
	s_cmp_ge_u32 s2, 0x100
	s_cbranch_scc0 .Lprio_p3
	s_setprio 1

; #define PG8_BAR __builtin_amdgcn_s_barrier()
; #define PG8_BAR __builtin_amdgcn_s_barrier()
; template <class Epi, class Sched>
; __device__ __forceinline__ void gemm_phase(LAS unsigned char* lds, const Gemm g, const Sched& S, const Epi& E) {
;     ...
;         if (wr == 0) PG8_BAR;
;         E(acc, cur, wr, wc, fr, fq);
.LBB0_834:
	s_and_b64 vcc, exec, s[10:11]
	s_cbranch_vccz .Leprio_gates
	s_setprio 1

; #define PG8_BAR __builtin_amdgcn_s_barrier()
; #define PG8_BAR __builtin_amdgcn_s_barrier()
; template <class Epi, class Sched>
; __device__ __forceinline__ void gemm_phase(LAS unsigned char* lds, const Gemm g, const Sched& S, const Epi& E) {
;     ...
;         if (wr == 0) PG8_BAR;
;         E(acc, cur, wr, wc, fr, fq);
.LBB0_1134:
	s_and_b64 vcc, exec, s[20:21]
	s_cbranch_vccz .Leprio_ffnup
	s_setprio 1
